# split-phase start-up grid sync: arrive at kernel start, wait for the release (and do the per-XCD registration) at the head of the first grid barrier instead of in front of the first phase
# baseline (speedup 1.0000x reference)
.LBB0_11:
	s_or_b64 exec, exec, s[6:7]
	v_and_b32_e32 v3, 0xffff0000, v3
	s_nop 1
	v_readfirstlane_b32 s6, v3
	s_nop 3
	v_writelane_b32 v255, s6, 61
.LBB0_14:
.LBB0_15:
	s_or_b64 exec, exec, s[4:5]
	s_mov_b32 s25, 0
	s_barrier
.LBB0_18:
	v_writelane_b32 v254, s0, 1
	s_mul_i32 s2, s15, s14
	s_lshr_b32 s3, s10, 6
	v_writelane_b32 v254, s1, 2
	s_load_dword s1, s[0:1], 0x120
	s_movk_i32 s82, 0x100
	v_mov_b32_e32 v3, 0
	s_mov_b32 s87, 0x7ffff
	v_mov_b32_e32 v191, 1
	s_waitcnt lgkmcnt(0)
	s_mul_i32 s0, s2, s1
	v_writelane_b32 v254, s0, 3
	s_lshl_b32 s0, s3, 14
	s_add_i32 s4, s0, 0
	s_bfe_u32 s2, s10, 0x20006
	s_cmpk_lt_u32 s10, 0x100
	s_cselect_b64 s[0:1], -1, 0
	v_writelane_b32 v254, s0, 4
	s_movk_i32 s91, 0x2000
	v_mov_b32_e32 v241, 0x358637bd
	v_writelane_b32 v254, s1, 5
	s_and_b64 s[0:1], s[0:1], exec
	s_cselect_b32 s0, 2, 0
	v_writelane_b32 v254, s0, 6
	s_and_b32 s0, s3, 0x3fffffc
	v_writelane_b32 v254, s0, 7
	s_lshl_b32 s5, s2, 7
	v_writelane_b32 v254, s5, 8
	s_lshl_b32 s0, s2, 6
	s_lshr_b32 s1, s10, 2
	v_writelane_b32 v254, s0, 9
	s_and_b32 s1, s1, 48
	s_lshr_b32 s0, s10, 8
	v_writelane_b32 v254, s1, 10
	s_lshl_b32 s54, s1, 7
	s_mul_i32 s1, s3, 0xffffc400
	s_add_i32 s57, s4, s1
	s_mul_i32 s1, s0, 0x5000
	s_add_i32 s1, s1, 0
	s_lshl_b32 s83, s0, 13
	v_writelane_b32 v254, s1, 11
	s_lshl_b32 s84, s2, 11
	s_lshl_b32 s33, s0, 14
	s_lshl_b32 s1, s2, 4
	s_cmp_eq_u32 s0, 1
	v_writelane_b32 v254, s1, 12
	s_cselect_b64 s[6:7], -1, 0
	v_writelane_b32 v254, s6, 13
	s_add_i32 s1, s3, 0xfffffe00
	s_lshl_b32 s0, s0, 6
	v_writelane_b32 v254, s7, 14
	v_writelane_b32 v254, s3, 15
	v_writelane_b32 v254, s1, 16
	v_writelane_b32 v254, s0, 17
	s_add_i32 s0, s5, s0
	v_writelane_b32 v254, s0, 18
	v_writelane_b32 v254, s4, 19
	s_add_i32 s0, s4, 0xa00
	v_writelane_b32 v254, s0, 20
	s_add_i32 s0, 0, 0x22000
	v_writelane_b32 v254, s0, 21
	s_add_i32 s0, 0, 0x22004
	v_writelane_b32 v254, s0, 22
	s_lshl_b32 s85, s2, 12
	v_cmp_eq_u32_e64 s[0:1], 0, v1
	s_lshl_b32 s86, s3, 12
	s_movk_i32 s69, 0x1200
	v_writelane_b32 v254, s0, 23
	s_mov_b32 s89, 0x7900000
	v_mov_b32_e32 v238, 0x1600
	v_writelane_b32 v254, s1, 24
	s_mov_b64 s[0:1], 0
	v_writelane_b32 v254, s0, 25
	v_mov_b32_e32 v239, 0xff800000
	v_mov_b32_e32 v190, 0x3ab69700
	v_writelane_b32 v254, s1, 26
	v_writelane_b32 v254, s67, 27
	v_writelane_b32 v254, s54, 28
	v_writelane_b32 v254, s83, 29
	v_writelane_b32 v254, s84, 30
	v_writelane_b32 v254, s85, 31
	v_mov_b32_e32 v240, 0x7f000000
	s_mov_b32 s97, 0xbe000000
	s_mov_b32 s95, 0x43000000
	s_mov_b32 s37, 0x42b17217
	s_mov_b32 s60, 0xc1880000
	s_mov_b64 s[0:1], -1
	s_mov_b64 s[62:63], 0x40000
	s_mov_b64 s[46:47], 0x80
	s_mov_b64 s[72:73], 0x40080
	s_mov_b64 s[74:75], 0x100
	s_mov_b32 s56, 0xbfb8aa3b
	s_mov_b32 s88, 0xbf317218
	s_mov_b32 s90, 0x3102e308
	s_mov_b32 s92, 0x395133b1
	s_mov_b32 s94, 0x3c0887f9
	s_mov_b32 s96, 0x3d2aaa81
	s_mov_b32 s36, 0x3e2aaaab
	s_mov_b32 s64, 0x3ab60b61
	s_mov_b32 s66, 0x3c088889
	s_mov_b32 s68, 0x3d2aaaab
	s_mov_b32 s20, s25
	v_writelane_b32 v254, s86, 32
	s_branch .LBB0_20

.LBB0_136:
	v_readlane_b32 s2, v254, 1
	v_readlane_b32 s3, v254, 2
	s_getreg_b32 s4, hwreg(HW_REG_XCC_ID, 0, 4)
	s_waitcnt vmcnt(0)
	s_waitcnt lgkmcnt(0)
	s_barrier
	s_mov_b64 s[0:1], exec
	v_readlane_b32 s6, v254, 23
	v_readlane_b32 s7, v254, 24
	s_and_b64 s[6:7], s[0:1], s[6:7]
	s_mov_b64 exec, s[6:7]
	s_cbranch_execz .LBB0_189
	s_load_dwordx2 s[6:7], s[2:3], 0x170
	s_load_dwordx2 s[8:9], s[2:3], 0x110
	v_readlane_b32 s5, v255, 61
	s_waitcnt lgkmcnt(0)
.Lmy_cg_wait:
	global_load_dword v0, v3, s[6:7] offset:32 sc1
	s_waitcnt vmcnt(0)
	v_and_b32_e32 v0, 0xffff0000, v0
	v_cmp_ne_u32_e32 vcc, s5, v0
	s_cbranch_vccnz .Lmy_cg_done
	s_sleep 1
	s_branch .Lmy_cg_wait
.Lmy_cg_done:
	s_lshl_b32 s5, s4, 8
	s_and_b32 s5, s5, 0xf00
	s_add_u32 s8, s8, s5
	s_addc_u32 s9, s9, 0
	v_mov_b32_e32 v0, 0x3780000
	v_mov_b32_e32 v2, 1
	global_atomic_add v0, v2, s[8:9] offset:1024
	v_readlane_b32 s5, v254, 21
	s_load_dwordx2 s[2:3], s[2:3], 0x110
	s_waitcnt vmcnt(0) expcnt(0) lgkmcnt(0)
	v_mov_b32_e32 v0, s5
	ds_read_b32 v2, v0
	v_readlane_b32 s5, v254, 22
	s_and_b32 s21, s4, 15
	s_waitcnt lgkmcnt(0)
	v_cmp_ne_u32_e32 vcc, 0, v2
	v_mov_b32_e32 v0, s5
	ds_read_b32 v0, v0
	s_cbranch_vccnz .LBB0_153
	s_add_u32 s4, s2, 0x3780200
	s_addc_u32 s5, s3, 0
	s_add_u32 s6, s2, 0x3780400
	s_addc_u32 s7, s3, 0
	s_add_u32 s8, s2, 0x3780500
	s_addc_u32 s9, s3, 0
	s_add_u32 s10, s2, 0x3780600
	s_addc_u32 s11, s3, 0
	s_add_u32 s12, s2, 0x3780700
	s_addc_u32 s13, s3, 0
	s_add_u32 s14, s2, 0x3780800
	s_addc_u32 s15, s3, 0
	s_add_u32 s16, s2, 0x3780900
	s_addc_u32 s17, s3, 0
	s_add_u32 s18, s2, 0x3780a00
	s_addc_u32 s19, s3, 0
	s_add_u32 s22, s2, 0x3780b00
	s_addc_u32 s23, s3, 0
	s_add_u32 s26, s2, 0x3780c00
	s_addc_u32 s27, s3, 0
	s_add_u32 s28, s2, 0x3780d00
	s_addc_u32 s29, s3, 0
	s_add_u32 s30, s2, 0x3780e00
	s_addc_u32 s31, s3, 0
	s_add_u32 s34, s2, 0x3780f00
	s_addc_u32 s35, s3, 0
	s_add_u32 s38, s2, 0x3781000
	s_addc_u32 s39, s3, 0
	s_add_u32 s40, s2, 0x3781100
	s_addc_u32 s41, s3, 0
	s_add_u32 s42, s2, 0x3781200
	s_addc_u32 s43, s3, 0
	s_add_u32 s44, s2, 0x3781300
	s_addc_u32 s45, s3, 0
	s_mov_b32 s24, 1
	s_branch .LBB0_141
